# EpiKV: hoist per-row ssq loads to one batch; attention PV before tile barrier
# speedup vs baseline: 1.0063x; 1.0038x over previous
; __device__ __forceinline__ unsigned pk4_fp8(float a, float b, float c, float d) { int w = 0; w = __builtin_amdgcn_cvt_pk_fp8_f32(a, b, w, false); w = __builtin_amdgcn_cvt_pk_fp8_f32(c, d, w, true); return (unsigned)w; }
; __device__ __forceinline__ unsigned char one_fp8(float a) { return (unsigned char)(__builtin_amdgcn_cvt_pk_fp8_f32(a, a, 0, false) & 0xFF); }
;     __device__ __forceinline__ void operator()(const AccT& acc, const Unit& u, int wr, int wc, int fr, int fq) const {
; #pragma unroll
;         for (int ai = 0; ai < 2; ++ai)
; #pragma unroll
;             for (int m = 0; m < 4; ++m) {
;                 const int row = EPI_ROW(u, ai, m);
;                 const float r = __builtin_amdgcn_rsqf(ssq_kv[row] * (1.0f / 128.0f) + RMS_EPS);
;                 const int c = wc * 32 + 8 * fq;
;                 const f32x4 k0 = acc[ai][0][m][0] * r, k1 = acc[ai][0][m][1] * r;
;                 u32x2 w; w.x = pk4_fp8(k0[0], k0[1], k0[2], k0[3]); w.y = pk4_fp8(k1[0], k1[1], k1[2], k1[3]);
;                 *(u32x2*)(Kb + (size_t)row * LDK + 192 * u.pn + c) = w;
;                 const int tile = row >> 6, k = row & 63, a = k >> 5, cc = k & 31, pos = 32 * ((cc >> 2) & 1) + 16 * a + (cc & 3) + 4 * (cc >> 3);
;                 unsigned char* vt = VT + ((size_t)(u.pn * (T / 64) + tile) * 128 + c) * 64 + (pos & 15);
; #pragma unroll
;                 for (int e = 0; e < 8; ++e) { const float v = (e < 4 ? acc[ai][1][m][0][e & 3] : acc[ai][1][m][1][e & 3]) * r;
;                     vt[e * 64 + ((((pos >> 4) ^ (((c + e) >> 2) & 3)) & 3) << 4)] = one_fp8(v); }
;             }
;     }
.LBB0_637:
	v_mov_b32_e32 v142, v216
	v_readlane_b32 s18, v255, 4
	v_ashrrev_i32_e32 v0, 2, v142
	v_and_b32_e32 v0, 0xffffffc0, v0
	v_and_b32_e32 v151, 15, v142
	v_lshl_add_u32 v152, s2, 8, v0
	v_or_b32_e32 v146, v152, v151
	v_ashrrev_i32_e32 v147, 31, v146
	v_lshl_add_u64 v[154:155], v[146:147], 2, s[38:39]
	flat_load_dword v166, v[154:155]
	flat_load_dword v167, v[154:155] offset:64
	flat_load_dword v168, v[154:155] offset:128
	flat_load_dword v169, v[154:155] offset:192
	flat_load_dword v170, v[154:155] offset:512
	flat_load_dword v171, v[154:155] offset:576
	flat_load_dword v172, v[154:155] offset:640
	flat_load_dword v173, v[154:155] offset:704
	v_mov_b32_e32 v154, v1
	v_mov_b32_e32 v155, v1
	v_readlane_b32 s19, v255, 5
	v_lshrrev_b32_e32 v157, 1, v142
	s_mul_i32 s0, s3, 0xc0
	s_lshl_b32 s2, s3, 9
	v_ashrrev_i32_e32 v144, 6, v152
	s_movk_i32 s13, 0x300
	v_bfe_u32 v156, v142, 4, 2
	v_and_b32_e32 v0, 0x60, v157
	s_ashr_i32 s1, s0, 31
	v_add_u32_e32 v144, s2, v144
	v_lshl_or_b32 v0, v156, 3, v0
	v_ashrrev_i32_e32 v145, 31, v144
	v_readlane_b32 s20, v255, 6
	v_lshlrev_b64 v[144:145], 13, v[144:145]
	v_readlane_b32 s21, v255, 7
	v_mov_b32_e32 v158, v1
	v_lshlrev_b32_e32 v156, 1, v156
	v_and_b32_e32 v153, 3, v142
	v_lshlrev_b32_e32 v142, 6, v0
	v_mov_b32_e32 v143, v1
	v_mov_b32_e32 v161, v1
	s_and_b64 vcc, exec, s[4:5]
	s_waitcnt vmcnt(0) lgkmcnt(0)
	v_fmamk_f32 v147, v166, 0x3c000000, v236
	v_rsq_f32_e32 v148, v147
	s_nop 0
	v_pk_mul_f32 v[126:127], v[126:127], v[148:149] op_sel_hi:[1,0]
	v_pk_mul_f32 v[122:123], v[122:123], v[148:149] op_sel_hi:[1,0]
	v_cvt_pk_fp8_f32 v154, v126, v127
	v_cvt_pk_fp8_f32 v155, v122, v123
	v_pk_mul_f32 v[128:129], v[128:129], v[148:149] op_sel_hi:[1,0]
	v_pk_mul_f32 v[124:125], v[124:125], v[148:149] op_sel_hi:[1,0]
	v_cvt_pk_fp8_f32 v154, v128, v129 op_sel:[0,0,1]
	v_cvt_pk_fp8_f32 v155, v124, v125 op_sel:[0,0,1]
	v_mov_b64_e32 v[122:123], s[18:19]
	v_mad_i64_i32 v[124:125], s[18:19], v146, s13, v[122:123]
	v_lshl_add_u64 v[124:125], v[124:125], 0, s[0:1]
	v_lshl_add_u64 v[124:125], v[124:125], 0, v[0:1]
	v_mul_f32_e32 v118, v118, v148
	flat_store_dwordx2 v[124:125], v[154:155]
	v_lshl_add_u64 v[124:125], s[20:21], 0, v[144:145]
	v_cvt_pk_fp8_f32 v158, v118, v118
	v_bitop3_b32 v118, v156, v157, 2 bitop3:0x28
	v_lshl_add_u64 v[144:145], v[124:125], 0, v[142:143]
	v_lshlrev_b32_e32 v124, 4, v118
	v_mul_f32_e32 v118, v119, v148
	v_and_or_b32 v128, v157, 4, v153
	v_mov_b32_e32 v129, v1
	v_cvt_pk_fp8_f32 v161, v118, v118
	v_bitop3_b32 v118, v156, v157, 2 bitop3:0x78
	v_lshl_add_u64 v[146:147], v[144:145], 0, v[128:129]
	v_and_b32_e32 v154, 2, v157
	v_mov_b32_e32 v125, v1
	v_lshlrev_b32_e32 v157, 4, v118
	v_lshl_add_u64 v[126:127], v[146:147], 0, v[124:125]
	v_or_b32_e32 v118, 64, v157
	v_mov_b32_e32 v119, v1
	flat_store_byte v[126:127], v158
	v_lshl_add_u64 v[158:159], v[146:147], 0, v[118:119]
	flat_store_byte v[158:159], v161
	v_mul_f32_e32 v120, v120, v148
	v_mov_b32_e32 v158, v1
	v_cvt_pk_fp8_f32 v158, v120, v120
	v_mul_f32_e32 v120, v121, v148
	v_and_b32_e32 v155, 2, v156
	v_mov_b32_e32 v121, v1
	flat_store_byte v[126:127], v158 offset:128
	v_mov_b32_e32 v158, v1
	v_cvt_pk_fp8_f32 v158, v120, v120
	v_or_b32_e32 v120, 0xc0, v157
	v_mul_f32_e32 v114, v114, v148
	v_mov_b32_e32 v157, v1
	v_lshl_add_u64 v[126:127], v[146:147], 0, v[120:121]
	v_cvt_pk_fp8_f32 v157, v114, v114
	v_bitop3_b32 v114, v155, v154, 1 bitop3:0x36
	flat_store_byte v[126:127], v158
	v_lshlrev_b32_e32 v126, 4, v114
	v_mul_f32_e32 v114, v115, v148
	v_mov_b32_e32 v115, v1
	v_cvt_pk_fp8_f32 v115, v114, v114
	v_mov_b32_e32 v127, v1
	v_lshl_add_u64 v[158:159], v[146:147], 0, v[126:127]
	v_mul_f32_e32 v114, v116, v148
	flat_store_byte v[158:159], v115 offset:320
	v_mov_b32_e32 v115, v1
	v_cvt_pk_fp8_f32 v115, v114, v114
	v_mul_f32_e32 v114, v117, v148
	v_or_b32_e32 v116, 16, v151
	flat_store_byte v[158:159], v157 offset:256
	flat_store_byte v[158:159], v115 offset:384
	v_mov_b32_e32 v115, v1
	v_cvt_pk_fp8_f32 v115, v114, v114
	v_or_b32_e32 v114, v152, v116
	flat_store_byte v[158:159], v115 offset:448
	v_ashrrev_i32_e32 v115, 31, v114
	v_lshl_add_u64 v[158:159], v[114:115], 2, s[38:39]
	v_mov_b32_e32 v158, v1
	v_mov_b32_e32 v159, v1
	v_fmamk_f32 v115, v167, 0x3c000000, v236
	v_rsq_f32_e32 v148, v115
	s_nop 0
	v_pk_mul_f32 v[110:111], v[110:111], v[148:149] op_sel_hi:[1,0]
	v_pk_mul_f32 v[106:107], v[106:107], v[148:149] op_sel_hi:[1,0]
	v_cvt_pk_fp8_f32 v158, v110, v111
	v_cvt_pk_fp8_f32 v159, v106, v107
	v_pk_mul_f32 v[112:113], v[112:113], v[148:149] op_sel_hi:[1,0]
	v_pk_mul_f32 v[108:109], v[108:109], v[148:149] op_sel_hi:[1,0]
	v_cvt_pk_fp8_f32 v158, v112, v113 op_sel:[0,0,1]
	v_cvt_pk_fp8_f32 v159, v108, v109 op_sel:[0,0,1]
	v_mad_i64_i32 v[106:107], s[18:19], v114, s13, v[122:123]
	v_lshl_add_u64 v[106:107], v[106:107], 0, s[0:1]
	v_lshl_add_u64 v[106:107], v[106:107], 0, v[0:1]
	v_mul_f32_e32 v102, v102, v148
	v_mov_b32_e32 v112, v1
	flat_store_dwordx2 v[106:107], v[158:159]
	v_lshrrev_b32_e32 v106, 1, v116
	v_cvt_pk_fp8_f32 v112, v102, v102
	v_and_or_b32 v106, v106, 12, v153
	v_mov_b32_e32 v107, v1
	v_lshl_add_u64 v[108:109], v[144:145], 0, v[106:107]
	v_lshl_add_u64 v[110:111], v[108:109], 0, v[124:125]
	flat_store_byte v[110:111], v112
	v_mul_f32_e32 v102, v103, v148
	v_mov_b32_e32 v112, v1
	v_cvt_pk_fp8_f32 v112, v102, v102
	v_lshl_add_u64 v[102:103], v[108:109], 0, v[118:119]
	v_mul_f32_e32 v98, v98, v148
	flat_store_byte v[102:103], v112
	v_mul_f32_e32 v102, v104, v148
	v_mov_b32_e32 v103, v1
	v_cvt_pk_fp8_f32 v103, v102, v102
	v_mul_f32_e32 v102, v105, v148
	v_mov_b32_e32 v104, v1
	v_cvt_pk_fp8_f32 v104, v102, v102
; __device__ __forceinline__ unsigned pk4_fp8(float a, float b, float c, float d) { int w = 0; w = __builtin_amdgcn_cvt_pk_fp8_f32(a, b, w, false); w = __builtin_amdgcn_cvt_pk_fp8_f32(c, d, w, true); return (unsigned)w; }
; __device__ __forceinline__ unsigned char one_fp8(float a) { return (unsigned char)(__builtin_amdgcn_cvt_pk_fp8_f32(a, a, 0, false) & 0xFF); }
;     __device__ __forceinline__ void operator()(const AccT& acc, const Unit& u, int wr, int wc, int fr, int fq) const {
; #pragma unroll
;         for (int ai = 0; ai < 2; ++ai)
; #pragma unroll
;             for (int m = 0; m < 4; ++m) {
;                 const int row = EPI_ROW(u, ai, m);
;                 const float r = __builtin_amdgcn_rsqf(ssq_kv[row] * (1.0f / 128.0f) + RMS_EPS);
;                 const int c = wc * 32 + 8 * fq;
;                 const f32x4 k0 = acc[ai][0][m][0] * r, k1 = acc[ai][0][m][1] * r;
;                 u32x2 w; w.x = pk4_fp8(k0[0], k0[1], k0[2], k0[3]); w.y = pk4_fp8(k1[0], k1[1], k1[2], k1[3]);
;                 *(u32x2*)(Kb + (size_t)row * LDK + 192 * u.pn + c) = w;
;                 const int tile = row >> 6, k = row & 63, a = k >> 5, cc = k & 31, pos = 32 * ((cc >> 2) & 1) + 16 * a + (cc & 3) + 4 * (cc >> 3);
;                 unsigned char* vt = VT + ((size_t)(u.pn * (T / 64) + tile) * 128 + c) * 64 + (pos & 15);
; #pragma unroll
;                 for (int e = 0; e < 8; ++e) { const float v = (e < 4 ? acc[ai][1][m][0][e & 3] : acc[ai][1][m][1][e & 3]) * r;
;                     vt[e * 64 + ((((pos >> 4) ^ (((c + e) >> 2) & 3)) & 3) << 4)] = one_fp8(v); }
;             }
;     }
	flat_store_byte v[110:111], v103 offset:128
	v_lshl_add_u64 v[102:103], v[108:109], 0, v[120:121]
	flat_store_byte v[102:103], v104
	v_mov_b32_e32 v104, v1
	v_cvt_pk_fp8_f32 v104, v98, v98
	v_mul_f32_e32 v98, v99, v148
	v_mov_b32_e32 v99, v1
	v_cvt_pk_fp8_f32 v99, v98, v98
	v_lshl_add_u64 v[102:103], v[108:109], 0, v[126:127]
	v_mul_f32_e32 v98, v100, v148
	flat_store_byte v[102:103], v104 offset:256
	flat_store_byte v[102:103], v99 offset:320
	v_mov_b32_e32 v99, v1
	v_cvt_pk_fp8_f32 v99, v98, v98
	v_mul_f32_e32 v98, v101, v148
	flat_store_byte v[102:103], v99 offset:384
	v_mov_b32_e32 v99, v1
	v_cvt_pk_fp8_f32 v99, v98, v98
	flat_store_byte v[102:103], v99 offset:448
	v_or_b32_e32 v99, 32, v151
	v_or_b32_e32 v100, v152, v99
	v_ashrrev_i32_e32 v101, 31, v100
	v_lshl_add_u64 v[102:103], v[100:101], 2, s[38:39]
	v_mov_b32_e32 v102, v1
	v_mov_b32_e32 v103, v1
	v_fmamk_f32 v98, v168, 0x3c000000, v236
	v_rsq_f32_e32 v98, v98
	s_nop 0
	v_pk_mul_f32 v[94:95], v[94:95], v[98:99] op_sel_hi:[1,0]
	v_pk_mul_f32 v[90:91], v[90:91], v[98:99] op_sel_hi:[1,0]
	v_cvt_pk_fp8_f32 v102, v94, v95
	v_cvt_pk_fp8_f32 v103, v90, v91
	v_pk_mul_f32 v[96:97], v[96:97], v[98:99] op_sel_hi:[1,0]
	v_pk_mul_f32 v[92:93], v[92:93], v[98:99] op_sel_hi:[1,0]
	v_cvt_pk_fp8_f32 v102, v96, v97 op_sel:[0,0,1]
	v_cvt_pk_fp8_f32 v103, v92, v93 op_sel:[0,0,1]
	v_mad_i64_i32 v[90:91], s[18:19], v100, s13, v[122:123]
	v_lshl_add_u64 v[90:91], v[90:91], 0, s[0:1]
	v_lshl_add_u64 v[90:91], v[90:91], 0, v[0:1]
	flat_store_dwordx2 v[90:91], v[102:103]
	v_or_b32_e32 v90, 1, v154
	v_mul_f32_e32 v86, v86, v98
	v_mov_b32_e32 v94, v1
	v_cvt_pk_fp8_f32 v94, v86, v86
	v_bitop3_b32 v86, v156, v90, 2 bitop3:0x6c
	v_lshlrev_b32_e32 v90, 4, v86
	v_mul_f32_e32 v86, v87, v98
	v_mov_b32_e32 v96, v1
	v_cvt_pk_fp8_f32 v96, v86, v86
	v_bitop3_b32 v86, v156, v154, 1 bitop3:0x1e
	v_mov_b32_e32 v91, v1
	v_lshlrev_b32_e32 v97, 4, v86
	v_lshl_add_u64 v[92:93], v[146:147], 0, v[90:91]
	v_or_b32_e32 v86, 64, v97
	v_mov_b32_e32 v87, v1
	flat_store_byte v[92:93], v94
	v_lshl_add_u64 v[94:95], v[146:147], 0, v[86:87]
	flat_store_byte v[94:95], v96
	v_mul_f32_e32 v88, v88, v98
	v_mov_b32_e32 v94, v1
	v_cvt_pk_fp8_f32 v94, v88, v88
	v_mul_f32_e32 v88, v89, v98
	v_mov_b32_e32 v89, v1
	v_mul_f32_e32 v82, v82, v98
	flat_store_byte v[92:93], v94 offset:128
	v_mov_b32_e32 v94, v1
	v_cvt_pk_fp8_f32 v94, v88, v88
	v_or_b32_e32 v88, 0xc0, v97
	v_mov_b32_e32 v96, v1
	v_lshl_add_u64 v[92:93], v[146:147], 0, v[88:89]
	v_cvt_pk_fp8_f32 v96, v82, v82
	v_bitop3_b32 v82, v155, v154, 1 bitop3:0x14
	flat_store_byte v[92:93], v94
	v_lshlrev_b32_e32 v92, 4, v82
	v_mul_f32_e32 v82, v83, v98
	v_mov_b32_e32 v83, v1
	v_cvt_pk_fp8_f32 v83, v82, v82
	v_mov_b32_e32 v93, v1
	v_lshl_add_u64 v[94:95], v[146:147], 0, v[92:93]
	v_mul_f32_e32 v82, v84, v98
	flat_store_byte v[94:95], v83 offset:320
	v_mov_b32_e32 v83, v1
	v_cvt_pk_fp8_f32 v83, v82, v82
	v_mul_f32_e32 v82, v85, v98
	flat_store_byte v[94:95], v96 offset:256
	v_mov_b32_e32 v96, v1
	flat_store_byte v[94:95], v83 offset:384
	v_mov_b32_e32 v83, v1
	v_cvt_pk_fp8_f32 v83, v82, v82
	v_or_b32_e32 v82, 48, v151
	v_or_b32_e32 v84, v152, v82
	v_ashrrev_i32_e32 v85, 31, v84
	flat_store_byte v[94:95], v83 offset:448
	v_lshl_add_u64 v[94:95], v[84:85], 2, s[38:39]
	v_mov_b32_e32 v97, v1
	v_fmamk_f32 v83, v169, 0x3c000000, v236
	v_rsq_f32_e32 v94, v83
	s_nop 0
	v_pk_mul_f32 v[78:79], v[78:79], v[94:95] op_sel_hi:[1,0]
	v_pk_mul_f32 v[74:75], v[74:75], v[94:95] op_sel_hi:[1,0]
	v_cvt_pk_fp8_f32 v96, v78, v79
	v_cvt_pk_fp8_f32 v97, v74, v75
	v_pk_mul_f32 v[80:81], v[80:81], v[94:95] op_sel_hi:[1,0]
	v_pk_mul_f32 v[76:77], v[76:77], v[94:95] op_sel_hi:[1,0]
	v_cvt_pk_fp8_f32 v96, v80, v81 op_sel:[0,0,1]
	v_cvt_pk_fp8_f32 v97, v76, v77 op_sel:[0,0,1]
	v_mad_i64_i32 v[74:75], s[18:19], v84, s13, v[122:123]
	v_lshl_add_u64 v[74:75], v[74:75], 0, s[0:1]
	v_lshl_add_u64 v[74:75], v[74:75], 0, v[0:1]
	v_mul_f32_e32 v70, v70, v94
	v_mov_b32_e32 v80, v1
	flat_store_dwordx2 v[74:75], v[96:97]
	v_lshrrev_b32_e32 v74, 1, v82
	v_cvt_pk_fp8_f32 v80, v70, v70
	v_and_or_b32 v74, v74, 12, v153
	v_mov_b32_e32 v75, v1
	v_lshl_add_u64 v[76:77], v[144:145], 0, v[74:75]
	v_lshl_add_u64 v[78:79], v[76:77], 0, v[90:91]
	flat_store_byte v[78:79], v80
	v_mul_f32_e32 v70, v71, v94
	v_mov_b32_e32 v80, v1
	v_cvt_pk_fp8_f32 v80, v70, v70
	v_lshl_add_u64 v[70:71], v[76:77], 0, v[86:87]
	v_mul_f32_e32 v66, v66, v94
	flat_store_byte v[70:71], v80
	v_mul_f32_e32 v70, v72, v94
	v_mov_b32_e32 v71, v1
	v_cvt_pk_fp8_f32 v71, v70, v70
	v_mul_f32_e32 v70, v73, v94
	v_mov_b32_e32 v72, v1
	v_cvt_pk_fp8_f32 v72, v70, v70
	flat_store_byte v[78:79], v71 offset:128
	v_lshl_add_u64 v[70:71], v[76:77], 0, v[88:89]
	flat_store_byte v[70:71], v72
	v_mov_b32_e32 v72, v1
	v_cvt_pk_fp8_f32 v72, v66, v66
	v_mul_f32_e32 v66, v67, v94
	v_mov_b32_e32 v67, v1
	v_cvt_pk_fp8_f32 v67, v66, v66
	v_lshl_add_u64 v[70:71], v[76:77], 0, v[92:93]
	v_mul_f32_e32 v66, v68, v94
	v_add_u32_e32 v68, 0x80, v152
	flat_store_byte v[70:71], v67 offset:320
	v_mov_b32_e32 v67, v1
	v_cvt_pk_fp8_f32 v67, v66, v66
	v_mul_f32_e32 v66, v69, v94
	flat_store_byte v[70:71], v72 offset:256
	v_mov_b32_e32 v76, v1
	flat_store_byte v[70:71], v67 offset:384
	v_mov_b32_e32 v67, v1
	v_cvt_pk_fp8_f32 v67, v66, v66
	v_mov_b32_e32 v77, v1
	v_ashrrev_i32_e32 v66, 6, v68
	v_add_u32_e32 v66, s2, v66
	flat_store_byte v[70:71], v67 offset:448
	v_or_b32_e32 v70, v68, v151
	v_ashrrev_i32_e32 v71, 31, v70
	v_lshl_add_u64 v[72:73], v[70:71], 2, s[38:39]
	v_ashrrev_i32_e32 v67, 31, v66
	v_lshlrev_b64 v[66:67], 13, v[66:67]
	v_fmamk_f32 v69, v170, 0x3c000000, v236
	v_rsq_f32_e32 v72, v69
	s_nop 0
; __device__ __forceinline__ unsigned pk4_fp8(float a, float b, float c, float d) { int w = 0; w = __builtin_amdgcn_cvt_pk_fp8_f32(a, b, w, false); w = __builtin_amdgcn_cvt_pk_fp8_f32(c, d, w, true); return (unsigned)w; }
; __device__ __forceinline__ unsigned char one_fp8(float a) { return (unsigned char)(__builtin_amdgcn_cvt_pk_fp8_f32(a, a, 0, false) & 0xFF); }
;     __device__ __forceinline__ void operator()(const AccT& acc, const Unit& u, int wr, int wc, int fr, int fq) const {
; #pragma unroll
;         for (int ai = 0; ai < 2; ++ai)
; #pragma unroll
;             for (int m = 0; m < 4; ++m) {
;                 const int row = EPI_ROW(u, ai, m);
;                 const float r = __builtin_amdgcn_rsqf(ssq_kv[row] * (1.0f / 128.0f) + RMS_EPS);
;                 const int c = wc * 32 + 8 * fq;
;                 const f32x4 k0 = acc[ai][0][m][0] * r, k1 = acc[ai][0][m][1] * r;
;                 u32x2 w; w.x = pk4_fp8(k0[0], k0[1], k0[2], k0[3]); w.y = pk4_fp8(k1[0], k1[1], k1[2], k1[3]);
;                 *(u32x2*)(Kb + (size_t)row * LDK + 192 * u.pn + c) = w;
;                 const int tile = row >> 6, k = row & 63, a = k >> 5, cc = k & 31, pos = 32 * ((cc >> 2) & 1) + 16 * a + (cc & 3) + 4 * (cc >> 3);
;                 unsigned char* vt = VT + ((size_t)(u.pn * (T / 64) + tile) * 128 + c) * 64 + (pos & 15);
; #pragma unroll
;                 for (int e = 0; e < 8; ++e) { const float v = (e < 4 ? acc[ai][1][m][0][e & 3] : acc[ai][1][m][1][e & 3]) * r;
;                     vt[e * 64 + ((((pos >> 4) ^ (((c + e) >> 2) & 3)) & 3) << 4)] = one_fp8(v); }
;             }
;     }
	v_pk_mul_f32 v[62:63], v[62:63], v[72:73] op_sel_hi:[1,0]
	v_pk_mul_f32 v[58:59], v[58:59], v[72:73] op_sel_hi:[1,0]
	v_cvt_pk_fp8_f32 v76, v62, v63
	v_cvt_pk_fp8_f32 v77, v58, v59
	v_pk_mul_f32 v[64:65], v[64:65], v[72:73] op_sel_hi:[1,0]
	v_pk_mul_f32 v[60:61], v[60:61], v[72:73] op_sel_hi:[1,0]
	v_cvt_pk_fp8_f32 v76, v64, v65 op_sel:[0,0,1]
	v_cvt_pk_fp8_f32 v77, v60, v61 op_sel:[0,0,1]
	v_mad_i64_i32 v[58:59], s[2:3], v70, s13, v[122:123]
	v_lshl_add_u64 v[58:59], v[58:59], 0, s[0:1]
	v_lshl_add_u64 v[58:59], v[58:59], 0, v[0:1]
	v_mul_f32_e32 v54, v54, v72
	v_mov_b32_e32 v64, v1
	flat_store_dwordx2 v[58:59], v[76:77]
	v_lshl_add_u64 v[58:59], s[20:21], 0, v[66:67]
	v_cvt_pk_fp8_f32 v64, v54, v54
	v_lshl_add_u64 v[58:59], v[58:59], 0, v[142:143]
	v_lshl_add_u64 v[60:61], v[58:59], 0, v[128:129]
	v_lshl_add_u64 v[62:63], v[60:61], 0, v[124:125]
	flat_store_byte v[62:63], v64
	v_mul_f32_e32 v54, v55, v72
	v_mov_b32_e32 v64, v1
	v_cvt_pk_fp8_f32 v64, v54, v54
	v_lshl_add_u64 v[54:55], v[60:61], 0, v[118:119]
	v_mul_f32_e32 v50, v50, v72
	flat_store_byte v[54:55], v64
	v_mul_f32_e32 v54, v56, v72
	v_mov_b32_e32 v55, v1
	v_cvt_pk_fp8_f32 v55, v54, v54
	v_mul_f32_e32 v54, v57, v72
	v_mov_b32_e32 v56, v1
	v_cvt_pk_fp8_f32 v56, v54, v54
	flat_store_byte v[62:63], v55 offset:128
	v_lshl_add_u64 v[54:55], v[60:61], 0, v[120:121]
	flat_store_byte v[54:55], v56
	v_mov_b32_e32 v56, v1
	v_cvt_pk_fp8_f32 v56, v50, v50
	v_mul_f32_e32 v50, v51, v72
	v_mov_b32_e32 v51, v1
	v_cvt_pk_fp8_f32 v51, v50, v50
	v_lshl_add_u64 v[54:55], v[60:61], 0, v[126:127]
	v_mul_f32_e32 v50, v52, v72
	flat_store_byte v[54:55], v56 offset:256
	flat_store_byte v[54:55], v51 offset:320
	v_mov_b32_e32 v51, v1
	v_cvt_pk_fp8_f32 v51, v50, v50
	v_mul_f32_e32 v50, v53, v72
	flat_store_byte v[54:55], v51 offset:384
	v_mov_b32_e32 v51, v1
	v_cvt_pk_fp8_f32 v51, v50, v50
	v_or_b32_e32 v50, v68, v116
	flat_store_byte v[54:55], v51 offset:448
	v_ashrrev_i32_e32 v51, 31, v50
	v_lshl_add_u64 v[52:53], v[50:51], 2, s[38:39]
	v_mov_b32_e32 v54, v1
	v_mov_b32_e32 v55, v1
	v_fmamk_f32 v51, v171, 0x3c000000, v236
	v_rsq_f32_e32 v52, v51
	s_nop 0
	v_pk_mul_f32 v[46:47], v[46:47], v[52:53] op_sel_hi:[1,0]
	v_pk_mul_f32 v[42:43], v[42:43], v[52:53] op_sel_hi:[1,0]
	v_cvt_pk_fp8_f32 v54, v46, v47
	v_cvt_pk_fp8_f32 v55, v42, v43
	v_pk_mul_f32 v[48:49], v[48:49], v[52:53] op_sel_hi:[1,0]
	v_pk_mul_f32 v[44:45], v[44:45], v[52:53] op_sel_hi:[1,0]
	v_cvt_pk_fp8_f32 v54, v48, v49 op_sel:[0,0,1]
	v_cvt_pk_fp8_f32 v55, v44, v45 op_sel:[0,0,1]
	v_mad_i64_i32 v[42:43], s[2:3], v50, s13, v[122:123]
	v_mul_f32_e32 v38, v38, v52
	v_mov_b32_e32 v46, v1
	v_lshl_add_u64 v[42:43], v[42:43], 0, s[0:1]
	v_cvt_pk_fp8_f32 v46, v38, v38
	v_lshl_add_u64 v[42:43], v[42:43], 0, v[0:1]
	flat_store_dwordx2 v[42:43], v[54:55]
	v_lshl_add_u64 v[42:43], v[58:59], 0, v[106:107]
	v_lshl_add_u64 v[44:45], v[42:43], 0, v[124:125]
	flat_store_byte v[44:45], v46
	v_mul_f32_e32 v38, v39, v52
	v_mov_b32_e32 v46, v1
	v_cvt_pk_fp8_f32 v46, v38, v38
	v_lshl_add_u64 v[38:39], v[42:43], 0, v[118:119]
	v_mul_f32_e32 v34, v34, v52
	flat_store_byte v[38:39], v46
	v_mul_f32_e32 v38, v40, v52
	v_mov_b32_e32 v39, v1
	v_cvt_pk_fp8_f32 v39, v38, v38
	v_mul_f32_e32 v38, v41, v52
	v_mov_b32_e32 v40, v1
	v_cvt_pk_fp8_f32 v40, v38, v38
	flat_store_byte v[44:45], v39 offset:128
	v_lshl_add_u64 v[38:39], v[42:43], 0, v[120:121]
	flat_store_byte v[38:39], v40
	v_mov_b32_e32 v40, v1
	v_cvt_pk_fp8_f32 v40, v34, v34
	v_mul_f32_e32 v34, v35, v52
	v_mov_b32_e32 v35, v1
	v_cvt_pk_fp8_f32 v35, v34, v34
	v_lshl_add_u64 v[38:39], v[42:43], 0, v[126:127]
	v_mul_f32_e32 v34, v36, v52
	flat_store_byte v[38:39], v40 offset:256
	flat_store_byte v[38:39], v35 offset:320
	v_mov_b32_e32 v35, v1
	v_cvt_pk_fp8_f32 v35, v34, v34
	v_mul_f32_e32 v34, v37, v52
	flat_store_byte v[38:39], v35 offset:384
	v_mov_b32_e32 v35, v1
	v_cvt_pk_fp8_f32 v35, v34, v34
	v_or_b32_e32 v34, v68, v99
	flat_store_byte v[38:39], v35 offset:448
	v_ashrrev_i32_e32 v35, 31, v34
; __device__ __forceinline__ unsigned pk4_fp8(float a, float b, float c, float d) { int w = 0; w = __builtin_amdgcn_cvt_pk_fp8_f32(a, b, w, false); w = __builtin_amdgcn_cvt_pk_fp8_f32(c, d, w, true); return (unsigned)w; }
; __device__ __forceinline__ unsigned char one_fp8(float a) { return (unsigned char)(__builtin_amdgcn_cvt_pk_fp8_f32(a, a, 0, false) & 0xFF); }
;     __device__ __forceinline__ void operator()(const AccT& acc, const Unit& u, int wr, int wc, int fr, int fq) const {
; #pragma unroll
;         for (int ai = 0; ai < 2; ++ai)
; #pragma unroll
;             for (int m = 0; m < 4; ++m) {
;                 const int row = EPI_ROW(u, ai, m);
;                 const float r = __builtin_amdgcn_rsqf(ssq_kv[row] * (1.0f / 128.0f) + RMS_EPS);
;                 const int c = wc * 32 + 8 * fq;
;                 const f32x4 k0 = acc[ai][0][m][0] * r, k1 = acc[ai][0][m][1] * r;
;                 u32x2 w; w.x = pk4_fp8(k0[0], k0[1], k0[2], k0[3]); w.y = pk4_fp8(k1[0], k1[1], k1[2], k1[3]);
;                 *(u32x2*)(Kb + (size_t)row * LDK + 192 * u.pn + c) = w;
;                 const int tile = row >> 6, k = row & 63, a = k >> 5, cc = k & 31, pos = 32 * ((cc >> 2) & 1) + 16 * a + (cc & 3) + 4 * (cc >> 3);
;                 unsigned char* vt = VT + ((size_t)(u.pn * (T / 64) + tile) * 128 + c) * 64 + (pos & 15);
; #pragma unroll
;                 for (int e = 0; e < 8; ++e) { const float v = (e < 4 ? acc[ai][1][m][0][e & 3] : acc[ai][1][m][1][e & 3]) * r;
;                     vt[e * 64 + ((((pos >> 4) ^ (((c + e) >> 2) & 3)) & 3) << 4)] = one_fp8(v); }
;             }
;     }
	v_lshl_add_u64 v[36:37], v[34:35], 2, s[38:39]
	v_mov_b32_e32 v38, v1
	v_mov_b32_e32 v39, v1
	v_fmamk_f32 v35, v172, 0x3c000000, v236
	v_rsq_f32_e32 v36, v35
	s_nop 0
	v_pk_mul_f32 v[30:31], v[30:31], v[36:37] op_sel_hi:[1,0]
	v_pk_mul_f32 v[26:27], v[26:27], v[36:37] op_sel_hi:[1,0]
	v_cvt_pk_fp8_f32 v38, v30, v31
	v_cvt_pk_fp8_f32 v39, v26, v27
	v_pk_mul_f32 v[32:33], v[32:33], v[36:37] op_sel_hi:[1,0]
	v_pk_mul_f32 v[28:29], v[28:29], v[36:37] op_sel_hi:[1,0]
	v_cvt_pk_fp8_f32 v38, v32, v33 op_sel:[0,0,1]
	v_cvt_pk_fp8_f32 v39, v28, v29 op_sel:[0,0,1]
	v_mul_f32_e32 v22, v22, v36
	v_mov_b32_e32 v28, v1
	v_mad_i64_i32 v[26:27], s[2:3], v34, s13, v[122:123]
	v_cvt_pk_fp8_f32 v28, v22, v22
	v_lshl_add_u64 v[26:27], v[26:27], 0, s[0:1]
	v_lshl_add_u64 v[26:27], v[26:27], 0, v[0:1]
	flat_store_dwordx2 v[26:27], v[38:39]
	v_lshl_add_u64 v[26:27], v[60:61], 0, v[90:91]
	flat_store_byte v[26:27], v28
	v_mul_f32_e32 v22, v23, v36
	v_mov_b32_e32 v28, v1
	v_cvt_pk_fp8_f32 v28, v22, v22
	v_lshl_add_u64 v[22:23], v[60:61], 0, v[86:87]
	v_mul_f32_e32 v18, v18, v36
	flat_store_byte v[22:23], v28
	v_mul_f32_e32 v22, v24, v36
	v_mov_b32_e32 v23, v1
	v_cvt_pk_fp8_f32 v23, v22, v22
	v_mul_f32_e32 v22, v25, v36
	v_mov_b32_e32 v24, v1
	v_cvt_pk_fp8_f32 v24, v22, v22
	flat_store_byte v[26:27], v23 offset:128
	v_lshl_add_u64 v[22:23], v[60:61], 0, v[88:89]
	flat_store_byte v[22:23], v24
	v_mov_b32_e32 v24, v1
	v_cvt_pk_fp8_f32 v24, v18, v18
	v_mul_f32_e32 v18, v19, v36
	v_mov_b32_e32 v19, v1
	v_cvt_pk_fp8_f32 v19, v18, v18
	v_lshl_add_u64 v[22:23], v[60:61], 0, v[92:93]
	v_mul_f32_e32 v18, v20, v36
	flat_store_byte v[22:23], v24 offset:256
	flat_store_byte v[22:23], v19 offset:320
	v_mov_b32_e32 v19, v1
	v_cvt_pk_fp8_f32 v19, v18, v18
	v_mul_f32_e32 v18, v21, v36
	flat_store_byte v[22:23], v19 offset:384
	v_mov_b32_e32 v19, v1
	v_cvt_pk_fp8_f32 v19, v18, v18
	v_or_b32_e32 v18, v68, v82
	flat_store_byte v[22:23], v19 offset:448
	v_ashrrev_i32_e32 v19, 31, v18
	v_lshl_add_u64 v[20:21], v[18:19], 2, s[38:39]
	v_mov_b32_e32 v22, v1
	v_mov_b32_e32 v23, v1
	v_fmamk_f32 v19, v173, 0x3c000000, v236
	v_rsq_f32_e32 v20, v19
	s_nop 0
	v_pk_mul_f32 v[14:15], v[14:15], v[20:21] op_sel_hi:[1,0]
	v_pk_mul_f32 v[10:11], v[10:11], v[20:21] op_sel_hi:[1,0]
	v_cvt_pk_fp8_f32 v22, v14, v15
	v_cvt_pk_fp8_f32 v23, v10, v11
	v_pk_mul_f32 v[16:17], v[16:17], v[20:21] op_sel_hi:[1,0]
	v_pk_mul_f32 v[12:13], v[12:13], v[20:21] op_sel_hi:[1,0]
	v_mad_i64_i32 v[10:11], s[2:3], v18, s13, v[122:123]
	v_cvt_pk_fp8_f32 v22, v16, v17 op_sel:[0,0,1]
	v_cvt_pk_fp8_f32 v23, v12, v13 op_sel:[0,0,1]
	v_lshl_add_u64 v[10:11], v[10:11], 0, s[0:1]
	v_lshl_add_u64 v[10:11], v[10:11], 0, v[0:1]
	v_mul_f32_e32 v0, v6, v20
	v_mov_b32_e32 v6, v1
	v_cvt_pk_fp8_f32 v6, v0, v0
	v_mul_f32_e32 v0, v7, v20
	v_mov_b32_e32 v14, v1
	v_cvt_pk_fp8_f32 v14, v0, v0
	flat_store_dwordx2 v[10:11], v[22:23]
	v_lshl_add_u64 v[10:11], v[58:59], 0, v[74:75]
	v_lshl_add_u64 v[12:13], v[10:11], 0, v[90:91]
	flat_store_byte v[12:13], v6
	v_lshl_add_u64 v[6:7], v[10:11], 0, v[86:87]
	flat_store_byte v[6:7], v14
	v_mul_f32_e32 v0, v8, v20
	v_mov_b32_e32 v6, v1
	v_cvt_pk_fp8_f32 v6, v0, v0
	v_mul_f32_e32 v0, v9, v20
	v_mov_b32_e32 v8, v1
	v_cvt_pk_fp8_f32 v8, v0, v0
	v_mul_f32_e32 v0, v2, v20
	v_mov_b32_e32 v2, v1
	v_cvt_pk_fp8_f32 v2, v0, v0
	flat_store_byte v[12:13], v6 offset:128
	v_lshl_add_u64 v[6:7], v[10:11], 0, v[88:89]
	flat_store_byte v[6:7], v8
	v_lshl_add_u64 v[6:7], v[10:11], 0, v[92:93]
	flat_store_byte v[6:7], v2 offset:256
	v_mul_f32_e32 v0, v3, v20
	v_mov_b32_e32 v2, v1
	v_cvt_pk_fp8_f32 v2, v0, v0
	v_mul_f32_e32 v0, v4, v20
	s_mov_b64 s[0:1], -1
	flat_store_byte v[6:7], v2 offset:320
	v_mov_b32_e32 v2, v1
	v_cvt_pk_fp8_f32 v2, v0, v0
	v_mul_f32_e32 v0, v5, v20
	flat_store_byte v[6:7], v2 offset:384
	v_mov_b32_e32 v2, v1
	v_cvt_pk_fp8_f32 v2, v0, v0
	flat_store_byte v[6:7], v2 offset:448
	s_cbranch_vccnz .LBB0_623
	s_andn2_b64 vcc, exec, s[6:7]
	s_cbranch_vccnz .LBB0_622
	s_barrier
	s_branch .LBB0_622
